# SwiGLU tile epilogue rewritten by hand: packed-f32 math, two interleaved dependency chains per quad, no s_nop padding (same f32 arithmetic, reassociated scales)
# speedup vs baseline: 1.0097x; 1.0097x over previous
; __device__ __forceinline__ float silu_f(float x) { return x * __builtin_amdgcn_rcpf(1.0f + __builtin_amdgcn_exp2f(-1.4426950408889634f * x)); }
;     __device__ __forceinline__ void operator()(const i32x4 (&acc)[2][2][4][2], const pg8::Unit& u, int wr, int wc, int fr_, int fq_, int tid) {
;         int fr = fr_, fq = fq_; asm volatile("" : "+v"(fr), "+v"(fq));
;         if (skip) return;
;         const int row0 = u.pm * 256 + wr * 64 + fr, col0 = u.pn * 128 + wc * 32 + 8 * fq;
;         const float* cp = cmax + u.pn * 256 + wc * 32 + 8 * fq;
;         f32x4 cs[2][2];
;         cs[0][0] = *(const f32x4*)(cp) * (1.0f / 127.0f); cs[0][1] = *(const f32x4*)(cp + 4) * (1.0f / 127.0f);
;         cs[1][0] = *(const f32x4*)(cp + 128) * (1.0f / 127.0f); cs[1][1] = *(const f32x4*)(cp + 132) * (1.0f / 127.0f);
; #pragma unroll
;         for (int ai = 0; ai < 2; ++ai)
; #pragma unroll
;             for (int m = 0; m < 4; ++m) {
;                 const int row = row0 + ai * 128 + m * 16;
;                 const float rs = rsl[wr * 64 + fr + ai * 128 + m * 16];
;                 f32x4 h[2];
; #pragma unroll
;                 for (int n = 0; n < 2; ++n) {
; #pragma unroll
;                     for (int i = 0; i < 4; ++i) { const float g = (float)acc[ai][0][m][n][i] * (rs * cs[0][n][i]), up = (float)acc[ai][1][m][n][i] * (rs * cs[1][n][i]); h[n][i] = silu_f(g) * up; } }
;                 *(u32x4*)(H + ((size_t)(u.pm * (DFF / 64) + (col0 >> 6)) * 256 + (size_t)(row & 255)) * 64 + (col0 & 63)) = pack8bf(h[0], h[1]);
;             }
;     }
.LBB0_166:
	s_mul_i32 s13, s20, 0x58
	v_lshrrev_b32_e32 v175, 4, v195
	s_lshl_b32 s22, s21, 10
	v_and_b32_e32 v174, 15, v195
	s_add_u32 s22, s45, s22
	s_addc_u32 s23, s46, 0
	v_lshlrev_b32_e32 v176, 4, v175
	v_lshlrev_b32_e32 v175, 5, v175
	global_load_dwordx4 v[216:219], v175, s[22:23]
	global_load_dwordx4 v[220:223], v175, s[22:23] offset:16
	global_load_dwordx4 v[224:227], v175, s[22:23] offset:512
	global_load_dwordx4 v[228:231], v175, s[22:23] offset:528
	v_add_u32_e32 v177, s40, v174
	v_lshl_add_u32 v174, v174, 2, s47
	ds_read_b32 v232, v174
	ds_read_b32 v234, v174 offset:64
	ds_read_b32 v236, v174 offset:128
	ds_read_b32 v238, v174 offset:192
	ds_read_b32 v240, v174 offset:512
	ds_read_b32 v242, v174 offset:576
	ds_read_b32 v244, v174 offset:640
	ds_read_b32 v246, v174 offset:704
	v_lshl_add_u32 v176, v177, 7, v176
	s_lshl_b32 s22, s21, 1
	s_add_i32 s13, s13, s22
	s_lshr_b32 s22, s41, 6
	s_add_i32 s13, s13, s22
	s_and_b32 s22, s41, 32
	s_lshl_b32 s22, s22, 1
	v_add_u32_e32 v176, s22, v176
	s_lshl_b32 s13, s13, 15
	s_add_u32 s20, s8, s13
	s_addc_u32 s21, s9, 0
	v_cvt_f32_i32_e32 v126, v126
	v_cvt_f32_i32_e32 v127, v127
	v_cvt_f32_i32_e32 v128, v128
	v_cvt_f32_i32_e32 v129, v129
	v_cvt_f32_i32_e32 v122, v122
	v_cvt_f32_i32_e32 v123, v123
	v_cvt_f32_i32_e32 v124, v124
	v_cvt_f32_i32_e32 v125, v125
	v_cvt_f32_i32_e32 v118, v118
	v_cvt_f32_i32_e32 v119, v119
	v_cvt_f32_i32_e32 v120, v120
	v_cvt_f32_i32_e32 v121, v121
	v_cvt_f32_i32_e32 v114, v114
	v_cvt_f32_i32_e32 v115, v115
	v_cvt_f32_i32_e32 v116, v116
	v_cvt_f32_i32_e32 v117, v117
	v_cvt_f32_i32_e32 v110, v110
	v_cvt_f32_i32_e32 v111, v111
	v_cvt_f32_i32_e32 v112, v112
	v_cvt_f32_i32_e32 v113, v113
	v_cvt_f32_i32_e32 v106, v106
	v_cvt_f32_i32_e32 v107, v107
	v_cvt_f32_i32_e32 v108, v108
	v_cvt_f32_i32_e32 v109, v109
	v_cvt_f32_i32_e32 v102, v102
	v_cvt_f32_i32_e32 v103, v103
	v_cvt_f32_i32_e32 v104, v104
	v_cvt_f32_i32_e32 v105, v105
	v_cvt_f32_i32_e32 v98, v98
	v_cvt_f32_i32_e32 v99, v99
	v_cvt_f32_i32_e32 v100, v100
	v_cvt_f32_i32_e32 v101, v101
	s_waitcnt vmcnt(0) lgkmcnt(0)
	v_pk_mul_f32 v[216:217], v[216:217], s[76:77] op_sel_hi:[1,0]
	v_pk_mul_f32 v[218:219], v[218:219], s[76:77] op_sel_hi:[1,0]
	v_pk_mul_f32 v[220:221], v[220:221], s[76:77] op_sel_hi:[1,0]
	v_pk_mul_f32 v[222:223], v[222:223], s[76:77] op_sel_hi:[1,0]
	v_pk_mul_f32 v[224:225], v[224:225], s[76:77] op_sel_hi:[1,0]
	v_pk_mul_f32 v[226:227], v[226:227], s[76:77] op_sel_hi:[1,0]
	v_pk_mul_f32 v[228:229], v[228:229], s[76:77] op_sel_hi:[1,0]
	v_pk_mul_f32 v[230:231], v[230:231], s[76:77] op_sel_hi:[1,0]
	v_mul_f32_e32 v233, v232, v232
	v_mul_f32_e32 v235, v234, v234
	v_mul_f32_e32 v237, v236, v236
	v_mul_f32_e32 v239, v238, v238
	v_mul_f32_e32 v241, v240, v240
	v_mul_f32_e32 v243, v242, v242
	v_mul_f32_e32 v245, v244, v244
	v_mul_f32_e32 v247, v246, v246
	v_mul_f32_e32 v232, 0xbfb8aa3b, v232
	v_mul_f32_e32 v234, 0xbfb8aa3b, v234
	v_mul_f32_e32 v236, 0xbfb8aa3b, v236
	v_mul_f32_e32 v238, 0xbfb8aa3b, v238
	v_mul_f32_e32 v240, 0xbfb8aa3b, v240
	v_mul_f32_e32 v242, 0xbfb8aa3b, v242
	v_mul_f32_e32 v244, 0xbfb8aa3b, v244
	v_mul_f32_e32 v246, 0xbfb8aa3b, v246
	v_cvt_f32_i32_e32 v94, v94
	v_cvt_f32_i32_e32 v95, v95
	v_cvt_f32_i32_e32 v96, v96
	v_cvt_f32_i32_e32 v97, v97
	v_cvt_f32_i32_e32 v90, v90
	v_cvt_f32_i32_e32 v91, v91
	v_cvt_f32_i32_e32 v92, v92
	v_cvt_f32_i32_e32 v93, v93
	v_cvt_f32_i32_e32 v86, v86
	v_cvt_f32_i32_e32 v87, v87
	v_cvt_f32_i32_e32 v88, v88
	v_cvt_f32_i32_e32 v89, v89
	v_cvt_f32_i32_e32 v82, v82
	v_cvt_f32_i32_e32 v83, v83
	v_cvt_f32_i32_e32 v84, v84
	v_cvt_f32_i32_e32 v85, v85
	v_pk_mul_f32 v[126:127], v[126:127], v[216:217]
	v_pk_mul_f32 v[128:129], v[128:129], v[218:219]
	v_pk_mul_f32 v[122:123], v[122:123], v[224:225]
	v_pk_mul_f32 v[124:125], v[124:125], v[226:227]
	v_pk_mul_f32 v[248:249], v[126:127], v[232:233] op_sel_hi:[1,0]
	v_pk_mul_f32 v[250:251], v[128:129], v[232:233] op_sel_hi:[1,0]
	v_pk_mul_f32 v[126:127], v[126:127], v[122:123]
	v_exp_f32_e32 v248, v248
	v_exp_f32_e32 v249, v249
	v_exp_f32_e32 v250, v250
	v_exp_f32_e32 v251, v251
	v_pk_mul_f32 v[128:129], v[128:129], v[124:125]
	v_pk_add_f32 v[248:249], v[248:249], 1.0 op_sel_hi:[1,0]
	v_pk_add_f32 v[250:251], v[250:251], 1.0 op_sel_hi:[1,0]
	v_rcp_f32_e32 v248, v248
	v_rcp_f32_e32 v249, v249
	v_rcp_f32_e32 v250, v250
	v_rcp_f32_e32 v251, v251
	v_pk_mul_f32 v[248:249], v[248:249], v[232:233] op_sel:[0,1] op_sel_hi:[1,1]
	v_pk_mul_f32 v[250:251], v[250:251], v[232:233] op_sel:[0,1] op_sel_hi:[1,1]
	v_pk_mul_f32 v[126:127], v[126:127], v[248:249]
	v_pk_mul_f32 v[128:129], v[128:129], v[250:251]
	v_cvt_pk_bf16_f32 v122, v126, v127
	v_cvt_pk_bf16_f32 v123, v128, v129
	v_pk_mul_f32 v[118:119], v[118:119], v[220:221]
	v_pk_mul_f32 v[120:121], v[120:121], v[222:223]
	v_pk_mul_f32 v[114:115], v[114:115], v[228:229]
	v_pk_mul_f32 v[116:117], v[116:117], v[230:231]
	v_pk_mul_f32 v[248:249], v[118:119], v[232:233] op_sel_hi:[1,0]
	v_pk_mul_f32 v[250:251], v[120:121], v[232:233] op_sel_hi:[1,0]
	v_pk_mul_f32 v[118:119], v[118:119], v[114:115]
	v_exp_f32_e32 v248, v248
	v_exp_f32_e32 v249, v249
	v_exp_f32_e32 v250, v250
	v_exp_f32_e32 v251, v251
	v_pk_mul_f32 v[120:121], v[120:121], v[116:117]
	v_pk_add_f32 v[248:249], v[248:249], 1.0 op_sel_hi:[1,0]
	v_pk_add_f32 v[250:251], v[250:251], 1.0 op_sel_hi:[1,0]
	v_rcp_f32_e32 v248, v248
	v_rcp_f32_e32 v249, v249
	v_rcp_f32_e32 v250, v250
	v_rcp_f32_e32 v251, v251
	v_pk_mul_f32 v[248:249], v[248:249], v[232:233] op_sel:[0,1] op_sel_hi:[1,1]
	v_pk_mul_f32 v[250:251], v[250:251], v[232:233] op_sel:[0,1] op_sel_hi:[1,1]
	v_pk_mul_f32 v[118:119], v[118:119], v[248:249]
	v_pk_mul_f32 v[120:121], v[120:121], v[250:251]
; __device__ __forceinline__ float silu_f(float x) { return x * __builtin_amdgcn_rcpf(1.0f + __builtin_amdgcn_exp2f(-1.4426950408889634f * x)); }
;     __device__ __forceinline__ void operator()(const i32x4 (&acc)[2][2][4][2], const pg8::Unit& u, int wr, int wc, int fr_, int fq_, int tid) {
;     ...
;             for (int m = 0; m < 4; ++m) {
;                 const int row = row0 + ai * 128 + m * 16;
;                 const float rs = rsl[wr * 64 + fr + ai * 128 + m * 16];
;                 f32x4 h[2];
; #pragma unroll
;                 for (int n = 0; n < 2; ++n) {
; #pragma unroll
;                     for (int i = 0; i < 4; ++i) { const float g = (float)acc[ai][0][m][n][i] * (rs * cs[0][n][i]), up = (float)acc[ai][1][m][n][i] * (rs * cs[1][n][i]); h[n][i] = silu_f(g) * up; } }
;                 *(u32x4*)(H + ((size_t)(u.pm * (DFF / 64) + (col0 >> 6)) * 256 + (size_t)(row & 255)) * 64 + (col0 & 63)) = pack8bf(h[0], h[1]);
;             }
;     }
	v_cvt_pk_bf16_f32 v124, v118, v119
	v_cvt_pk_bf16_f32 v125, v120, v121
	s_mov_b64 s[22:23], s[20:21]
	global_store_dwordx4 v176, v[122:125], s[22:23]
	v_cvt_f32_i32_e32 v78, v78
	v_cvt_f32_i32_e32 v79, v79
	v_cvt_f32_i32_e32 v80, v80
	v_cvt_f32_i32_e32 v81, v81
	v_cvt_f32_i32_e32 v74, v74
	v_cvt_f32_i32_e32 v75, v75
	v_cvt_f32_i32_e32 v76, v76
	v_cvt_f32_i32_e32 v77, v77
	v_cvt_f32_i32_e32 v70, v70
	v_cvt_f32_i32_e32 v71, v71
	v_cvt_f32_i32_e32 v72, v72
	v_cvt_f32_i32_e32 v73, v73
	v_cvt_f32_i32_e32 v66, v66
	v_cvt_f32_i32_e32 v67, v67
	v_cvt_f32_i32_e32 v68, v68
	v_cvt_f32_i32_e32 v69, v69
	v_pk_mul_f32 v[110:111], v[110:111], v[216:217]
	v_pk_mul_f32 v[112:113], v[112:113], v[218:219]
	v_pk_mul_f32 v[106:107], v[106:107], v[224:225]
	v_pk_mul_f32 v[108:109], v[108:109], v[226:227]
	v_pk_mul_f32 v[248:249], v[110:111], v[234:235] op_sel_hi:[1,0]
	v_pk_mul_f32 v[250:251], v[112:113], v[234:235] op_sel_hi:[1,0]
	v_pk_mul_f32 v[110:111], v[110:111], v[106:107]
	v_exp_f32_e32 v248, v248
	v_exp_f32_e32 v249, v249
	v_exp_f32_e32 v250, v250
	v_exp_f32_e32 v251, v251
	v_pk_mul_f32 v[112:113], v[112:113], v[108:109]
	v_pk_add_f32 v[248:249], v[248:249], 1.0 op_sel_hi:[1,0]
	v_pk_add_f32 v[250:251], v[250:251], 1.0 op_sel_hi:[1,0]
	v_rcp_f32_e32 v248, v248
	v_rcp_f32_e32 v249, v249
	v_rcp_f32_e32 v250, v250
	v_rcp_f32_e32 v251, v251
	v_pk_mul_f32 v[248:249], v[248:249], v[234:235] op_sel:[0,1] op_sel_hi:[1,1]
	v_pk_mul_f32 v[250:251], v[250:251], v[234:235] op_sel:[0,1] op_sel_hi:[1,1]
	v_pk_mul_f32 v[110:111], v[110:111], v[248:249]
	v_pk_mul_f32 v[112:113], v[112:113], v[250:251]
	v_cvt_pk_bf16_f32 v106, v110, v111
	v_cvt_pk_bf16_f32 v107, v112, v113
	v_pk_mul_f32 v[102:103], v[102:103], v[220:221]
	v_pk_mul_f32 v[104:105], v[104:105], v[222:223]
	v_pk_mul_f32 v[98:99], v[98:99], v[228:229]
	v_pk_mul_f32 v[100:101], v[100:101], v[230:231]
	v_pk_mul_f32 v[248:249], v[102:103], v[234:235] op_sel_hi:[1,0]
	v_pk_mul_f32 v[250:251], v[104:105], v[234:235] op_sel_hi:[1,0]
	v_pk_mul_f32 v[102:103], v[102:103], v[98:99]
	v_exp_f32_e32 v248, v248
	v_exp_f32_e32 v249, v249
	v_exp_f32_e32 v250, v250
	v_exp_f32_e32 v251, v251
	v_pk_mul_f32 v[104:105], v[104:105], v[100:101]
	v_pk_add_f32 v[248:249], v[248:249], 1.0 op_sel_hi:[1,0]
	v_pk_add_f32 v[250:251], v[250:251], 1.0 op_sel_hi:[1,0]
	v_rcp_f32_e32 v248, v248
	v_rcp_f32_e32 v249, v249
	v_rcp_f32_e32 v250, v250
	v_rcp_f32_e32 v251, v251
	v_pk_mul_f32 v[248:249], v[248:249], v[234:235] op_sel:[0,1] op_sel_hi:[1,1]
	v_pk_mul_f32 v[250:251], v[250:251], v[234:235] op_sel:[0,1] op_sel_hi:[1,1]
	v_pk_mul_f32 v[102:103], v[102:103], v[248:249]
	v_pk_mul_f32 v[104:105], v[104:105], v[250:251]
	v_cvt_pk_bf16_f32 v108, v102, v103
	v_cvt_pk_bf16_f32 v109, v104, v105
	global_store_dwordx4 v176, v[106:109], s[22:23] offset:2048
	v_cvt_f32_i32_e32 v62, v62
	v_cvt_f32_i32_e32 v63, v63
	v_cvt_f32_i32_e32 v64, v64
	v_cvt_f32_i32_e32 v65, v65
	v_cvt_f32_i32_e32 v58, v58
	v_cvt_f32_i32_e32 v59, v59
	v_cvt_f32_i32_e32 v60, v60
	v_cvt_f32_i32_e32 v61, v61
	v_cvt_f32_i32_e32 v54, v54
	v_cvt_f32_i32_e32 v55, v55
	v_cvt_f32_i32_e32 v56, v56
	v_cvt_f32_i32_e32 v57, v57
	v_cvt_f32_i32_e32 v50, v50
	v_cvt_f32_i32_e32 v51, v51
	v_cvt_f32_i32_e32 v52, v52
	v_cvt_f32_i32_e32 v53, v53
	v_pk_mul_f32 v[94:95], v[94:95], v[216:217]
	v_pk_mul_f32 v[96:97], v[96:97], v[218:219]
	v_pk_mul_f32 v[90:91], v[90:91], v[224:225]
	v_pk_mul_f32 v[92:93], v[92:93], v[226:227]
	v_pk_mul_f32 v[248:249], v[94:95], v[236:237] op_sel_hi:[1,0]
	v_pk_mul_f32 v[250:251], v[96:97], v[236:237] op_sel_hi:[1,0]
	v_pk_mul_f32 v[94:95], v[94:95], v[90:91]
	v_exp_f32_e32 v248, v248
	v_exp_f32_e32 v249, v249
	v_exp_f32_e32 v250, v250
	v_exp_f32_e32 v251, v251
	v_pk_mul_f32 v[96:97], v[96:97], v[92:93]
	v_pk_add_f32 v[248:249], v[248:249], 1.0 op_sel_hi:[1,0]
	v_pk_add_f32 v[250:251], v[250:251], 1.0 op_sel_hi:[1,0]
	v_rcp_f32_e32 v248, v248
	v_rcp_f32_e32 v249, v249
	v_rcp_f32_e32 v250, v250
	v_rcp_f32_e32 v251, v251
	v_pk_mul_f32 v[248:249], v[248:249], v[236:237] op_sel:[0,1] op_sel_hi:[1,1]
	v_pk_mul_f32 v[250:251], v[250:251], v[236:237] op_sel:[0,1] op_sel_hi:[1,1]
	v_pk_mul_f32 v[94:95], v[94:95], v[248:249]
	v_pk_mul_f32 v[96:97], v[96:97], v[250:251]
	v_cvt_pk_bf16_f32 v90, v94, v95
	v_cvt_pk_bf16_f32 v91, v96, v97
	v_pk_mul_f32 v[86:87], v[86:87], v[220:221]
	v_pk_mul_f32 v[88:89], v[88:89], v[222:223]
	v_pk_mul_f32 v[82:83], v[82:83], v[228:229]
	v_pk_mul_f32 v[84:85], v[84:85], v[230:231]
	v_pk_mul_f32 v[248:249], v[86:87], v[236:237] op_sel_hi:[1,0]
	v_pk_mul_f32 v[250:251], v[88:89], v[236:237] op_sel_hi:[1,0]
	v_pk_mul_f32 v[86:87], v[86:87], v[82:83]
	v_exp_f32_e32 v248, v248
	v_exp_f32_e32 v249, v249
	v_exp_f32_e32 v250, v250
	v_exp_f32_e32 v251, v251
	v_pk_mul_f32 v[88:89], v[88:89], v[84:85]
	v_pk_add_f32 v[248:249], v[248:249], 1.0 op_sel_hi:[1,0]
	v_pk_add_f32 v[250:251], v[250:251], 1.0 op_sel_hi:[1,0]
	v_rcp_f32_e32 v248, v248
	v_rcp_f32_e32 v249, v249
	v_rcp_f32_e32 v250, v250
	v_rcp_f32_e32 v251, v251
	v_pk_mul_f32 v[248:249], v[248:249], v[236:237] op_sel:[0,1] op_sel_hi:[1,1]
	v_pk_mul_f32 v[250:251], v[250:251], v[236:237] op_sel:[0,1] op_sel_hi:[1,1]
	v_pk_mul_f32 v[86:87], v[86:87], v[248:249]
	v_pk_mul_f32 v[88:89], v[88:89], v[250:251]
	v_cvt_pk_bf16_f32 v92, v86, v87
	v_cvt_pk_bf16_f32 v93, v88, v89
	s_add_u32 s22, s20, 0x1000
	s_addc_u32 s23, s21, 0
	global_store_dwordx4 v176, v[90:93], s[22:23]
	v_cvt_f32_i32_e32 v46, v46
	v_cvt_f32_i32_e32 v47, v47
	v_cvt_f32_i32_e32 v48, v48
	v_cvt_f32_i32_e32 v49, v49
	v_cvt_f32_i32_e32 v42, v42
	v_cvt_f32_i32_e32 v43, v43
	v_cvt_f32_i32_e32 v44, v44
	v_cvt_f32_i32_e32 v45, v45
; __device__ __forceinline__ float silu_f(float x) { return x * __builtin_amdgcn_rcpf(1.0f + __builtin_amdgcn_exp2f(-1.4426950408889634f * x)); }
;     __device__ __forceinline__ void operator()(const i32x4 (&acc)[2][2][4][2], const pg8::Unit& u, int wr, int wc, int fr_, int fq_, int tid) {
;     ...
;             for (int m = 0; m < 4; ++m) {
;                 const int row = row0 + ai * 128 + m * 16;
;                 const float rs = rsl[wr * 64 + fr + ai * 128 + m * 16];
;                 f32x4 h[2];
; #pragma unroll
;                 for (int n = 0; n < 2; ++n) {
; #pragma unroll
;                     for (int i = 0; i < 4; ++i) { const float g = (float)acc[ai][0][m][n][i] * (rs * cs[0][n][i]), up = (float)acc[ai][1][m][n][i] * (rs * cs[1][n][i]); h[n][i] = silu_f(g) * up; } }
;                 *(u32x4*)(H + ((size_t)(u.pm * (DFF / 64) + (col0 >> 6)) * 256 + (size_t)(row & 255)) * 64 + (col0 & 63)) = pack8bf(h[0], h[1]);
;             }
;     }
	v_cvt_f32_i32_e32 v38, v38
	v_cvt_f32_i32_e32 v39, v39
	v_cvt_f32_i32_e32 v40, v40
	v_cvt_f32_i32_e32 v41, v41
	v_cvt_f32_i32_e32 v34, v34
	v_cvt_f32_i32_e32 v35, v35
	v_cvt_f32_i32_e32 v36, v36
	v_cvt_f32_i32_e32 v37, v37
	v_pk_mul_f32 v[78:79], v[78:79], v[216:217]
	v_pk_mul_f32 v[80:81], v[80:81], v[218:219]
	v_pk_mul_f32 v[74:75], v[74:75], v[224:225]
	v_pk_mul_f32 v[76:77], v[76:77], v[226:227]
	v_pk_mul_f32 v[248:249], v[78:79], v[238:239] op_sel_hi:[1,0]
	v_pk_mul_f32 v[250:251], v[80:81], v[238:239] op_sel_hi:[1,0]
	v_pk_mul_f32 v[78:79], v[78:79], v[74:75]
	v_exp_f32_e32 v248, v248
	v_exp_f32_e32 v249, v249
	v_exp_f32_e32 v250, v250
	v_exp_f32_e32 v251, v251
	v_pk_mul_f32 v[80:81], v[80:81], v[76:77]
	v_pk_add_f32 v[248:249], v[248:249], 1.0 op_sel_hi:[1,0]
	v_pk_add_f32 v[250:251], v[250:251], 1.0 op_sel_hi:[1,0]
	v_rcp_f32_e32 v248, v248
	v_rcp_f32_e32 v249, v249
	v_rcp_f32_e32 v250, v250
	v_rcp_f32_e32 v251, v251
	v_pk_mul_f32 v[248:249], v[248:249], v[238:239] op_sel:[0,1] op_sel_hi:[1,1]
	v_pk_mul_f32 v[250:251], v[250:251], v[238:239] op_sel:[0,1] op_sel_hi:[1,1]
	v_pk_mul_f32 v[78:79], v[78:79], v[248:249]
	v_pk_mul_f32 v[80:81], v[80:81], v[250:251]
	v_cvt_pk_bf16_f32 v74, v78, v79
	v_cvt_pk_bf16_f32 v75, v80, v81
	v_pk_mul_f32 v[70:71], v[70:71], v[220:221]
	v_pk_mul_f32 v[72:73], v[72:73], v[222:223]
	v_pk_mul_f32 v[66:67], v[66:67], v[228:229]
	v_pk_mul_f32 v[68:69], v[68:69], v[230:231]
	v_pk_mul_f32 v[248:249], v[70:71], v[238:239] op_sel_hi:[1,0]
	v_pk_mul_f32 v[250:251], v[72:73], v[238:239] op_sel_hi:[1,0]
	v_pk_mul_f32 v[70:71], v[70:71], v[66:67]
	v_exp_f32_e32 v248, v248
	v_exp_f32_e32 v249, v249
	v_exp_f32_e32 v250, v250
	v_exp_f32_e32 v251, v251
	v_pk_mul_f32 v[72:73], v[72:73], v[68:69]
	v_pk_add_f32 v[248:249], v[248:249], 1.0 op_sel_hi:[1,0]
	v_pk_add_f32 v[250:251], v[250:251], 1.0 op_sel_hi:[1,0]
	v_rcp_f32_e32 v248, v248
	v_rcp_f32_e32 v249, v249
	v_rcp_f32_e32 v250, v250
	v_rcp_f32_e32 v251, v251
	v_pk_mul_f32 v[248:249], v[248:249], v[238:239] op_sel:[0,1] op_sel_hi:[1,1]
	v_pk_mul_f32 v[250:251], v[250:251], v[238:239] op_sel:[0,1] op_sel_hi:[1,1]
	v_pk_mul_f32 v[70:71], v[70:71], v[248:249]
	v_pk_mul_f32 v[72:73], v[72:73], v[250:251]
	v_cvt_pk_bf16_f32 v76, v70, v71
	v_cvt_pk_bf16_f32 v77, v72, v73
	global_store_dwordx4 v176, v[74:77], s[22:23] offset:2048
	v_cvt_f32_i32_e32 v30, v30
	v_cvt_f32_i32_e32 v31, v31
	v_cvt_f32_i32_e32 v32, v32
	v_cvt_f32_i32_e32 v33, v33
	v_cvt_f32_i32_e32 v26, v26
	v_cvt_f32_i32_e32 v27, v27
	v_cvt_f32_i32_e32 v28, v28
	v_cvt_f32_i32_e32 v29, v29
	v_cvt_f32_i32_e32 v22, v22
	v_cvt_f32_i32_e32 v23, v23
	v_cvt_f32_i32_e32 v24, v24
	v_cvt_f32_i32_e32 v25, v25
	v_cvt_f32_i32_e32 v18, v18
	v_cvt_f32_i32_e32 v19, v19
	v_cvt_f32_i32_e32 v20, v20
	v_cvt_f32_i32_e32 v21, v21
	v_pk_mul_f32 v[62:63], v[62:63], v[216:217]
	v_pk_mul_f32 v[64:65], v[64:65], v[218:219]
	v_pk_mul_f32 v[58:59], v[58:59], v[224:225]
	v_pk_mul_f32 v[60:61], v[60:61], v[226:227]
	v_pk_mul_f32 v[248:249], v[62:63], v[240:241] op_sel_hi:[1,0]
	v_pk_mul_f32 v[250:251], v[64:65], v[240:241] op_sel_hi:[1,0]
	v_pk_mul_f32 v[62:63], v[62:63], v[58:59]
	v_exp_f32_e32 v248, v248
	v_exp_f32_e32 v249, v249
	v_exp_f32_e32 v250, v250
	v_exp_f32_e32 v251, v251
	v_pk_mul_f32 v[64:65], v[64:65], v[60:61]
	v_pk_add_f32 v[248:249], v[248:249], 1.0 op_sel_hi:[1,0]
	v_pk_add_f32 v[250:251], v[250:251], 1.0 op_sel_hi:[1,0]
	v_rcp_f32_e32 v248, v248
	v_rcp_f32_e32 v249, v249
	v_rcp_f32_e32 v250, v250
	v_rcp_f32_e32 v251, v251
	v_pk_mul_f32 v[248:249], v[248:249], v[240:241] op_sel:[0,1] op_sel_hi:[1,1]
	v_pk_mul_f32 v[250:251], v[250:251], v[240:241] op_sel:[0,1] op_sel_hi:[1,1]
	v_pk_mul_f32 v[62:63], v[62:63], v[248:249]
	v_pk_mul_f32 v[64:65], v[64:65], v[250:251]
	v_cvt_pk_bf16_f32 v58, v62, v63
	v_cvt_pk_bf16_f32 v59, v64, v65
	v_pk_mul_f32 v[54:55], v[54:55], v[220:221]
	v_pk_mul_f32 v[56:57], v[56:57], v[222:223]
	v_pk_mul_f32 v[50:51], v[50:51], v[228:229]
	v_pk_mul_f32 v[52:53], v[52:53], v[230:231]
	v_pk_mul_f32 v[248:249], v[54:55], v[240:241] op_sel_hi:[1,0]
	v_pk_mul_f32 v[250:251], v[56:57], v[240:241] op_sel_hi:[1,0]
	v_pk_mul_f32 v[54:55], v[54:55], v[50:51]
	v_exp_f32_e32 v248, v248
	v_exp_f32_e32 v249, v249
	v_exp_f32_e32 v250, v250
	v_exp_f32_e32 v251, v251
	v_pk_mul_f32 v[56:57], v[56:57], v[52:53]
	v_pk_add_f32 v[248:249], v[248:249], 1.0 op_sel_hi:[1,0]
	v_pk_add_f32 v[250:251], v[250:251], 1.0 op_sel_hi:[1,0]
	v_rcp_f32_e32 v248, v248
	v_rcp_f32_e32 v249, v249
	v_rcp_f32_e32 v250, v250
	v_rcp_f32_e32 v251, v251
	v_pk_mul_f32 v[248:249], v[248:249], v[240:241] op_sel:[0,1] op_sel_hi:[1,1]
	v_pk_mul_f32 v[250:251], v[250:251], v[240:241] op_sel:[0,1] op_sel_hi:[1,1]
	v_pk_mul_f32 v[54:55], v[54:55], v[248:249]
	v_pk_mul_f32 v[56:57], v[56:57], v[250:251]
	v_cvt_pk_bf16_f32 v60, v54, v55
	v_cvt_pk_bf16_f32 v61, v56, v57
	s_add_u32 s22, s20, 0x4000
	s_addc_u32 s23, s21, 0
	global_store_dwordx4 v176, v[58:61], s[22:23]
	v_cvt_f32_i32_e32 v14, v14
	v_cvt_f32_i32_e32 v15, v15
	v_cvt_f32_i32_e32 v16, v16
	v_cvt_f32_i32_e32 v17, v17
	v_cvt_f32_i32_e32 v10, v10
	v_cvt_f32_i32_e32 v11, v11
	v_cvt_f32_i32_e32 v12, v12
	v_cvt_f32_i32_e32 v13, v13
	v_cvt_f32_i32_e32 v6, v6
	v_cvt_f32_i32_e32 v7, v7
	v_cvt_f32_i32_e32 v8, v8
	v_cvt_f32_i32_e32 v9, v9
	v_cvt_f32_i32_e32 v2, v2
	v_cvt_f32_i32_e32 v3, v3
	v_cvt_f32_i32_e32 v4, v4
	v_cvt_f32_i32_e32 v5, v5
	v_pk_mul_f32 v[46:47], v[46:47], v[216:217]
	v_pk_mul_f32 v[48:49], v[48:49], v[218:219]
	v_pk_mul_f32 v[42:43], v[42:43], v[224:225]
	v_pk_mul_f32 v[44:45], v[44:45], v[226:227]
	v_pk_mul_f32 v[248:249], v[46:47], v[242:243] op_sel_hi:[1,0]
; __device__ __forceinline__ float silu_f(float x) { return x * __builtin_amdgcn_rcpf(1.0f + __builtin_amdgcn_exp2f(-1.4426950408889634f * x)); }
;     __device__ __forceinline__ void operator()(const i32x4 (&acc)[2][2][4][2], const pg8::Unit& u, int wr, int wc, int fr_, int fq_, int tid) {
;     ...
;             for (int m = 0; m < 4; ++m) {
;                 const int row = row0 + ai * 128 + m * 16;
;                 const float rs = rsl[wr * 64 + fr + ai * 128 + m * 16];
;                 f32x4 h[2];
; #pragma unroll
;                 for (int n = 0; n < 2; ++n) {
; #pragma unroll
;                     for (int i = 0; i < 4; ++i) { const float g = (float)acc[ai][0][m][n][i] * (rs * cs[0][n][i]), up = (float)acc[ai][1][m][n][i] * (rs * cs[1][n][i]); h[n][i] = silu_f(g) * up; } }
;                 *(u32x4*)(H + ((size_t)(u.pm * (DFF / 64) + (col0 >> 6)) * 256 + (size_t)(row & 255)) * 64 + (col0 & 63)) = pack8bf(h[0], h[1]);
;             }
;     }
	v_pk_mul_f32 v[250:251], v[48:49], v[242:243] op_sel_hi:[1,0]
	v_pk_mul_f32 v[46:47], v[46:47], v[42:43]
	v_exp_f32_e32 v248, v248
	v_exp_f32_e32 v249, v249
	v_exp_f32_e32 v250, v250
	v_exp_f32_e32 v251, v251
	v_pk_mul_f32 v[48:49], v[48:49], v[44:45]
	v_pk_add_f32 v[248:249], v[248:249], 1.0 op_sel_hi:[1,0]
	v_pk_add_f32 v[250:251], v[250:251], 1.0 op_sel_hi:[1,0]
	v_rcp_f32_e32 v248, v248
	v_rcp_f32_e32 v249, v249
	v_rcp_f32_e32 v250, v250
	v_rcp_f32_e32 v251, v251
	v_pk_mul_f32 v[248:249], v[248:249], v[242:243] op_sel:[0,1] op_sel_hi:[1,1]
	v_pk_mul_f32 v[250:251], v[250:251], v[242:243] op_sel:[0,1] op_sel_hi:[1,1]
	v_pk_mul_f32 v[46:47], v[46:47], v[248:249]
	v_pk_mul_f32 v[48:49], v[48:49], v[250:251]
	v_cvt_pk_bf16_f32 v42, v46, v47
	v_cvt_pk_bf16_f32 v43, v48, v49
	v_pk_mul_f32 v[38:39], v[38:39], v[220:221]
	v_pk_mul_f32 v[40:41], v[40:41], v[222:223]
	v_pk_mul_f32 v[34:35], v[34:35], v[228:229]
	v_pk_mul_f32 v[36:37], v[36:37], v[230:231]
	v_pk_mul_f32 v[248:249], v[38:39], v[242:243] op_sel_hi:[1,0]
	v_pk_mul_f32 v[250:251], v[40:41], v[242:243] op_sel_hi:[1,0]
	v_pk_mul_f32 v[38:39], v[38:39], v[34:35]
	v_exp_f32_e32 v248, v248
	v_exp_f32_e32 v249, v249
	v_exp_f32_e32 v250, v250
	v_exp_f32_e32 v251, v251
	v_pk_mul_f32 v[40:41], v[40:41], v[36:37]
	v_pk_add_f32 v[248:249], v[248:249], 1.0 op_sel_hi:[1,0]
	v_pk_add_f32 v[250:251], v[250:251], 1.0 op_sel_hi:[1,0]
	v_rcp_f32_e32 v248, v248
	v_rcp_f32_e32 v249, v249
	v_rcp_f32_e32 v250, v250
	v_rcp_f32_e32 v251, v251
	v_pk_mul_f32 v[248:249], v[248:249], v[242:243] op_sel:[0,1] op_sel_hi:[1,1]
	v_pk_mul_f32 v[250:251], v[250:251], v[242:243] op_sel:[0,1] op_sel_hi:[1,1]
	v_pk_mul_f32 v[38:39], v[38:39], v[248:249]
	v_pk_mul_f32 v[40:41], v[40:41], v[250:251]
	v_cvt_pk_bf16_f32 v44, v38, v39
	v_cvt_pk_bf16_f32 v45, v40, v41
	global_store_dwordx4 v176, v[42:45], s[22:23] offset:2048
	v_pk_mul_f32 v[30:31], v[30:31], v[216:217]
	v_pk_mul_f32 v[32:33], v[32:33], v[218:219]
	v_pk_mul_f32 v[26:27], v[26:27], v[224:225]
	v_pk_mul_f32 v[28:29], v[28:29], v[226:227]
	v_pk_mul_f32 v[248:249], v[30:31], v[244:245] op_sel_hi:[1,0]
	v_pk_mul_f32 v[250:251], v[32:33], v[244:245] op_sel_hi:[1,0]
	v_pk_mul_f32 v[30:31], v[30:31], v[26:27]
	v_exp_f32_e32 v248, v248
	v_exp_f32_e32 v249, v249
	v_exp_f32_e32 v250, v250
	v_exp_f32_e32 v251, v251
	v_pk_mul_f32 v[32:33], v[32:33], v[28:29]
	v_pk_add_f32 v[248:249], v[248:249], 1.0 op_sel_hi:[1,0]
	v_pk_add_f32 v[250:251], v[250:251], 1.0 op_sel_hi:[1,0]
	v_rcp_f32_e32 v248, v248
	v_rcp_f32_e32 v249, v249
	v_rcp_f32_e32 v250, v250
	v_rcp_f32_e32 v251, v251
	v_pk_mul_f32 v[248:249], v[248:249], v[244:245] op_sel:[0,1] op_sel_hi:[1,1]
	v_pk_mul_f32 v[250:251], v[250:251], v[244:245] op_sel:[0,1] op_sel_hi:[1,1]
	v_pk_mul_f32 v[30:31], v[30:31], v[248:249]
	v_pk_mul_f32 v[32:33], v[32:33], v[250:251]
	v_cvt_pk_bf16_f32 v26, v30, v31
	v_cvt_pk_bf16_f32 v27, v32, v33
	v_pk_mul_f32 v[22:23], v[22:23], v[220:221]
	v_pk_mul_f32 v[24:25], v[24:25], v[222:223]
	v_pk_mul_f32 v[18:19], v[18:19], v[228:229]
	v_pk_mul_f32 v[20:21], v[20:21], v[230:231]
	v_pk_mul_f32 v[248:249], v[22:23], v[244:245] op_sel_hi:[1,0]
	v_pk_mul_f32 v[250:251], v[24:25], v[244:245] op_sel_hi:[1,0]
	v_pk_mul_f32 v[22:23], v[22:23], v[18:19]
	v_exp_f32_e32 v248, v248
	v_exp_f32_e32 v249, v249
	v_exp_f32_e32 v250, v250
	v_exp_f32_e32 v251, v251
	v_pk_mul_f32 v[24:25], v[24:25], v[20:21]
	v_pk_add_f32 v[248:249], v[248:249], 1.0 op_sel_hi:[1,0]
	v_pk_add_f32 v[250:251], v[250:251], 1.0 op_sel_hi:[1,0]
	v_rcp_f32_e32 v248, v248
	v_rcp_f32_e32 v249, v249
	v_rcp_f32_e32 v250, v250
	v_rcp_f32_e32 v251, v251
	v_pk_mul_f32 v[248:249], v[248:249], v[244:245] op_sel:[0,1] op_sel_hi:[1,1]
	v_pk_mul_f32 v[250:251], v[250:251], v[244:245] op_sel:[0,1] op_sel_hi:[1,1]
	v_pk_mul_f32 v[22:23], v[22:23], v[248:249]
	v_pk_mul_f32 v[24:25], v[24:25], v[250:251]
	v_cvt_pk_bf16_f32 v28, v22, v23
	v_cvt_pk_bf16_f32 v29, v24, v25
	s_add_u32 s22, s20, 0x5000
	s_addc_u32 s23, s21, 0
	global_store_dwordx4 v176, v[26:29], s[22:23]
	v_pk_mul_f32 v[14:15], v[14:15], v[216:217]
	v_pk_mul_f32 v[16:17], v[16:17], v[218:219]
	v_pk_mul_f32 v[10:11], v[10:11], v[224:225]
	v_pk_mul_f32 v[12:13], v[12:13], v[226:227]
	v_pk_mul_f32 v[248:249], v[14:15], v[246:247] op_sel_hi:[1,0]
	v_pk_mul_f32 v[250:251], v[16:17], v[246:247] op_sel_hi:[1,0]
	v_pk_mul_f32 v[14:15], v[14:15], v[10:11]
	v_exp_f32_e32 v248, v248
	v_exp_f32_e32 v249, v249
	v_exp_f32_e32 v250, v250
	v_exp_f32_e32 v251, v251
	v_pk_mul_f32 v[16:17], v[16:17], v[12:13]
	v_pk_add_f32 v[248:249], v[248:249], 1.0 op_sel_hi:[1,0]
	v_pk_add_f32 v[250:251], v[250:251], 1.0 op_sel_hi:[1,0]
	v_rcp_f32_e32 v248, v248
	v_rcp_f32_e32 v249, v249
	v_rcp_f32_e32 v250, v250
	v_rcp_f32_e32 v251, v251
	v_pk_mul_f32 v[248:249], v[248:249], v[246:247] op_sel:[0,1] op_sel_hi:[1,1]
	v_pk_mul_f32 v[250:251], v[250:251], v[246:247] op_sel:[0,1] op_sel_hi:[1,1]
	v_pk_mul_f32 v[14:15], v[14:15], v[248:249]
	v_pk_mul_f32 v[16:17], v[16:17], v[250:251]
	v_cvt_pk_bf16_f32 v10, v14, v15
	v_cvt_pk_bf16_f32 v11, v16, v17
	v_pk_mul_f32 v[6:7], v[6:7], v[220:221]
	v_pk_mul_f32 v[8:9], v[8:9], v[222:223]
	v_pk_mul_f32 v[2:3], v[2:3], v[228:229]
	v_pk_mul_f32 v[4:5], v[4:5], v[230:231]
	v_pk_mul_f32 v[248:249], v[6:7], v[246:247] op_sel_hi:[1,0]
	v_pk_mul_f32 v[250:251], v[8:9], v[246:247] op_sel_hi:[1,0]
	v_pk_mul_f32 v[6:7], v[6:7], v[2:3]
	v_exp_f32_e32 v248, v248
	v_exp_f32_e32 v249, v249
	v_exp_f32_e32 v250, v250
	v_exp_f32_e32 v251, v251
	v_pk_mul_f32 v[8:9], v[8:9], v[4:5]
	v_pk_add_f32 v[248:249], v[248:249], 1.0 op_sel_hi:[1,0]
	v_pk_add_f32 v[250:251], v[250:251], 1.0 op_sel_hi:[1,0]
	v_rcp_f32_e32 v248, v248
	v_rcp_f32_e32 v249, v249
	v_rcp_f32_e32 v250, v250
	v_rcp_f32_e32 v251, v251
	v_pk_mul_f32 v[248:249], v[248:249], v[246:247] op_sel:[0,1] op_sel_hi:[1,1]
	v_pk_mul_f32 v[250:251], v[250:251], v[246:247] op_sel:[0,1] op_sel_hi:[1,1]
	v_pk_mul_f32 v[6:7], v[6:7], v[248:249]
	v_pk_mul_f32 v[8:9], v[8:9], v[250:251]
	v_cvt_pk_bf16_f32 v12, v6, v7
	v_cvt_pk_bf16_f32 v13, v8, v9
	global_store_dwordx4 v176, v[10:13], s[22:23] offset:2048
	s_mov_b64 s[20:21], -1
	s_andn2_b64 vcc, exec, s[4:5]
	s_cbranch_vccnz .LBB0_159
	s_andn2_b64 vcc, exec, s[6:7]
	s_cbranch_vccnz .LBB0_158
	s_barrier
	s_branch .LBB0_158
